# P0 part-0 transposes (w_in, w_out, w_ple_proj, gate blocks, cache_v) also moved to the LDS-free 32x64-tile routine
# speedup vs baseline: 1.0353x; 1.0032x over previous
.LBB0_24:
	s_load_dwordx16 s[44:59], s[0:1], 0x0
	v_writelane_b32 v249, s12, 5
	s_lshr_b32 s90, s68, 6
	s_cmp_lt_i32 s26, 1
	s_cselect_b64 s[6:7], -1, 0
	s_waitcnt lgkmcnt(0)
	v_writelane_b32 v249, s44, 6
	s_cmp_gt_i32 s27, 0
	v_and_b32_e32 v0, 64, v184
	v_writelane_b32 v249, s45, 7
	v_writelane_b32 v249, s46, 8
	v_writelane_b32 v249, s47, 9
	v_writelane_b32 v249, s48, 10
	v_writelane_b32 v249, s49, 11
	v_writelane_b32 v249, s50, 12
	v_writelane_b32 v249, s51, 13
	v_writelane_b32 v249, s52, 14
	v_writelane_b32 v249, s53, 15
	v_writelane_b32 v249, s54, 16
	v_writelane_b32 v249, s55, 17
	v_writelane_b32 v249, s56, 18
	v_writelane_b32 v249, s57, 19
	v_writelane_b32 v249, s58, 20
	v_writelane_b32 v249, s59, 21
	s_load_dwordx16 s[44:59], s[0:1], 0x40
	v_add_u32_e32 v0, 64, v0
	v_xor_b32_e32 v1, 1, v184
	v_cmp_lt_i32_e32 vcc, v1, v0
	s_waitcnt lgkmcnt(0)
	v_writelane_b32 v249, s44, 22
	v_cndmask_b32_e32 v1, v184, v1, vcc
	s_nop 0
	v_writelane_b32 v249, s45, 23
	v_writelane_b32 v249, s46, 24
	v_writelane_b32 v249, s47, 25
	v_writelane_b32 v249, s48, 26
	v_writelane_b32 v249, s49, 27
	v_writelane_b32 v249, s50, 28
	v_writelane_b32 v249, s51, 29
	v_writelane_b32 v249, s52, 30
	v_writelane_b32 v249, s53, 31
	v_writelane_b32 v249, s54, 32
	v_writelane_b32 v249, s55, 33
	v_writelane_b32 v249, s56, 34
	v_writelane_b32 v249, s57, 35
	v_writelane_b32 v249, s58, 36
	v_writelane_b32 v249, s59, 37
	s_load_dwordx16 s[48:63], s[0:1], 0x80
	s_cselect_b64 s[0:1], -1, 0
	s_lshl_b32 s3, s2, 3
	v_writelane_b32 v249, s3, 38
	s_add_i32 s30, s90, s3
	s_lshl_b32 s3, s90, 14
	s_and_b64 s[0:1], s[6:7], s[0:1]
	s_lshl_b32 s10, s74, 3
	v_writelane_b32 v249, s3, 39
	s_add_i32 s3, s3, 0
	s_add_u32 s80, s24, 0x149c5000
	s_addc_u32 s81, s25, 0
	s_add_u32 s94, s24, 0x1a10000
	s_addc_u32 s95, s25, 0
	s_add_u32 s70, s24, 0x1a00000
	s_addc_u32 s71, s25, 0
	s_add_u32 s8, s24, 0x1980000
	v_writelane_b32 v249, s3, 40
	s_addc_u32 s9, s25, 0
	v_writelane_b32 v249, s8, 41
	v_lshlrev_b32_e32 v218, 2, v1
	v_xor_b32_e32 v1, 2, v184
	v_writelane_b32 v249, s9, 42
	s_add_u32 s8, s24, 0x1780000
	s_addc_u32 s9, s25, 0
	v_writelane_b32 v249, s8, 43
	v_cmp_lt_i32_e32 vcc, v1, v0
	s_nop 0
	v_writelane_b32 v249, s9, 44
	s_add_u32 s8, s24, 0x1200000
	s_addc_u32 s9, s25, 0
	v_writelane_b32 v249, s8, 45
	v_cndmask_b32_e32 v1, v184, v1, vcc
	v_lshlrev_b32_e32 v219, 2, v1
	v_writelane_b32 v249, s9, 46
	s_add_u32 s8, s24, 0x700000
	s_addc_u32 s9, s25, 0
	v_writelane_b32 v249, s8, 47
	v_xor_b32_e32 v1, 4, v184
	v_cmp_lt_i32_e32 vcc, v1, v0
	v_writelane_b32 v249, s9, 48
	v_writelane_b32 v249, s36, 49
	s_add_u32 s8, s24, 0x500000
	s_addc_u32 s9, s25, 0
	v_writelane_b32 v249, s37, 50
	v_writelane_b32 v249, s38, 51
	v_writelane_b32 v249, s39, 52
	v_writelane_b32 v249, s40, 53
	v_writelane_b32 v249, s41, 54
	v_writelane_b32 v249, s42, 55
	v_writelane_b32 v249, s43, 56
	s_waitcnt lgkmcnt(0)
	v_writelane_b32 v249, s48, 57
	s_cmp_lg_u64 s[38:39], 0
	v_cndmask_b32_e32 v1, v184, v1, vcc
	v_writelane_b32 v248, s55, 0
	v_writelane_b32 v248, s56, 1
	v_writelane_b32 v248, s57, 2
	v_writelane_b32 v249, s49, 58
	v_writelane_b32 v248, s58, 3
	v_writelane_b32 v249, s50, 59
	v_writelane_b32 v248, s59, 4
	v_writelane_b32 v249, s51, 60
	v_writelane_b32 v248, s60, 5
	s_cselect_b64 s[88:89], -1, 0
	v_writelane_b32 v249, s52, 61
	v_writelane_b32 v248, s61, 6
	s_cmp_lg_u64 s[58:59], 0
	v_lshlrev_b32_e32 v220, 2, v1
	v_xor_b32_e32 v1, 8, v184
	v_writelane_b32 v249, s53, 62
	v_writelane_b32 v248, s62, 7
	s_cselect_b64 s[34:35], -1, 0
	s_cmp_lt_i32 s30, 0x8400
	v_cmp_lt_i32_e32 vcc, v1, v0
	v_writelane_b32 v249, s54, 63
	v_writelane_b32 v248, s63, 8
	s_mov_b32 s54, s10
	s_cselect_b64 s[96:97], -1, 0
	s_add_u32 s10, s24, 0x1ddc5000
	v_cndmask_b32_e32 v1, v184, v1, vcc
	s_addc_u32 s11, s25, 0
	v_lshlrev_b32_e32 v221, 2, v1
	v_xor_b32_e32 v1, 16, v184
	v_writelane_b32 v248, s10, 9
	v_cmp_lt_i32_e32 vcc, v1, v0
	s_nop 0
	v_writelane_b32 v248, s11, 10
	s_add_u32 s10, s24, 0x2145000
	v_cndmask_b32_e32 v1, v184, v1, vcc
	s_addc_u32 s11, s25, 0
	v_lshlrev_b32_e32 v222, 2, v1
	v_xor_b32_e32 v1, 32, v184
	v_writelane_b32 v248, s10, 11
	v_cmp_lt_i32_e32 vcc, v1, v0
	s_nop 0
	v_writelane_b32 v248, s11, 12
	v_cndmask_b32_e32 v0, v184, v1, vcc
	s_andn2_b64 vcc, exec, s[0:1]
	v_lshlrev_b32_e32 v223, 2, v0
	v_writelane_b32 v248, s8, 13
	s_nop 1
	v_writelane_b32 v248, s9, 14
	s_cbranch_vccnz .LBB0_140
	s_cmpk_gt_i32 s30, 0x179f
	v_mov_b32_e32 v0, v184
	s_cbranch_scc1 .LBB0_132
	v_writelane_b32 v251, s0, 0
	v_writelane_b32 v251, s1, 1
	v_writelane_b32 v251, s2, 2
	v_writelane_b32 v251, s3, 3
	v_writelane_b32 v251, s4, 4
	v_writelane_b32 v251, s5, 5
	v_writelane_b32 v251, s6, 6
	v_writelane_b32 v251, s7, 7
	v_writelane_b32 v251, s8, 8
	v_writelane_b32 v251, s9, 9
	v_writelane_b32 v251, s10, 10
	v_writelane_b32 v251, s11, 11
	v_writelane_b32 v251, s12, 12
	v_writelane_b32 v251, s13, 13
	v_writelane_b32 v251, s14, 14
	v_writelane_b32 v251, s15, 15
	v_writelane_b32 v251, s16, 16
	v_writelane_b32 v251, s17, 17
	v_writelane_b32 v251, s18, 18
	v_writelane_b32 v251, s19, 19
	s_mov_b32 s0, s30
	s_mov_b32 s1, s54
	v_and_b32_e32 v2, 15, v184
	v_lshrrev_b32_e32 v1, 4, v184
	v_lshlrev_b32_e32 v0, 4, v2
	v_lshlrev_b32_e32 v2, 2, v2
	v_lshlrev_b32_e32 v3, 5, v1
	v_lshlrev_b32_e32 v6, 4, v1
.Ltp0_loop:
	s_cmp_lt_u32 s0, 6048
	s_cbranch_scc0 .Ltp0_done
	s_add_u32 s2, s0, s1
	s_cmp_lt_u32 s2, 6048
	s_cselect_b32 s2, s2, s0
	s_add_u32 s3, s0, s1
	s_add_u32 s3, s3, s1
	s_cmp_lt_u32 s3, 6048
	s_cselect_b32 s3, s3, s0
	s_cmp_lt_u32 s0, 1280
	s_cbranch_scc0 .Ltp01_c1
	s_mov_b32 s15, s0
	s_mul_hi_u32 s16, s15, 0x6666667
	s_mul_i32 s17, s16, 40
	s_sub_u32 s17, s15, s17
	v_readlane_b32 s4, v249, 24
	v_readlane_b32 s5, v249, 25
	s_mov_b32 s6, 0x2800
	s_mul_i32 s18, s16, 0x50000
	s_lshl_b32 s15, s17, 8
	s_add_u32 s18, s18, s15
	s_add_u32 s4, s4, s18
	s_addc_u32 s5, s5, 0
	s_branch .Ltp01_end
.Ltp01_c1:
	s_cmp_lt_u32 s0, 1792
	s_cbranch_scc0 .Ltp01_c2
	s_sub_u32 s15, s0, 0x500
	s_lshr_b32 s16, s15, 4
	s_and_b32 s17, s15, 15
	v_readlane_b32 s4, v248, 1
	v_readlane_b32 s5, v248, 2
	s_mov_b32 s6, 0x1000
	s_mul_i32 s18, s16, 0x20000
	s_lshl_b32 s15, s17, 8
	s_add_u32 s18, s18, s15
	s_add_u32 s4, s4, s18
	s_addc_u32 s5, s5, 0
	s_branch .Ltp01_end
.Ltp01_c2:
	s_cmp_lt_u32 s0, 1920
	s_cbranch_scc0 .Ltp01_c3
	s_sub_u32 s15, s0, 0x700
	s_lshr_b32 s16, s15, 4
	s_and_b32 s17, s15, 15
	v_readlane_b32 s4, v249, 55
	v_readlane_b32 s5, v249, 56
	s_mov_b32 s6, 0x1000
	s_mul_i32 s18, s16, 0x20000
	s_lshl_b32 s15, s17, 8
	s_add_u32 s18, s18, s15
	s_add_u32 s4, s4, s18
	s_addc_u32 s5, s5, 0
	s_branch .Ltp01_end
.Ltp01_c3:
	s_cmp_lt_u32 s0, 1936
	s_cbranch_scc0 .Ltp01_c4
	s_sub_u32 s15, s0, 0x780
	s_lshr_b32 s19, s15, 1
	s_bfe_u32 s16, s15, 0x10000
	s_mov_b32 s17, 0
	v_readlane_b32 s4, v249, 30
	v_readlane_b32 s5, v249, 31
	s_mov_b32 s6, 0x100
	s_mul_i32 s18, s16, 0x2000
	s_lshl_b32 s15, s17, 8
	s_add_u32 s18, s18, s15
	s_mul_i32 s15, s19, 0x4000
	s_add_u32 s18, s18, s15
	s_add_u32 s4, s4, s18
	s_addc_u32 s5, s5, 0
	s_branch .Ltp01_end
.Ltp01_c4:
	s_cmp_lt_u32 s0, 1952
	s_cbranch_scc0 .Ltp01_c5
	s_sub_u32 s15, s0, 0x790
	s_lshr_b32 s19, s15, 1
	s_bfe_u32 s16, s15, 0x10000
	s_mov_b32 s17, 0
	v_readlane_b32 s4, v249, 34
	v_readlane_b32 s5, v249, 35
	s_mov_b32 s6, 0x100
	s_mul_i32 s18, s16, 0x2000
	s_lshl_b32 s15, s17, 8
	s_add_u32 s18, s18, s15
	s_mul_i32 s15, s19, 0x4000
	s_add_u32 s18, s18, s15
	s_add_u32 s4, s4, s18
	s_addc_u32 s5, s5, 0
	s_branch .Ltp01_end
.Ltp01_c5:
	s_sub_u32 s15, s0, 0x7a0
	s_lshr_b32 s19, s15, 7
	s_bfe_u32 s16, s15, 0x40003
	s_and_b32 s17, s15, 7
	v_readlane_b32 s4, v249, 16
	v_readlane_b32 s5, v249, 17
	s_mov_b32 s6, 0x800
	s_mul_i32 s18, s16, 0x10000
	s_lshl_b32 s15, s17, 8
	s_add_u32 s18, s18, s15
	s_mul_i32 s15, s19, 0x100000
	s_add_u32 s18, s18, s15
	s_add_u32 s4, s4, s18
	s_addc_u32 s5, s5, 0
.Ltp01_end:
	s_lshl_b32 s7, s6, 3
	s_nop 0
	v_mad_u32_u24 v4, v1, s7, v0
	s_nop 3
	global_load_dwordx4 v[16:19], v4, s[4:5]
	s_add_u32 s4, s4, s6
	s_addc_u32 s5, s5, 0
	global_load_dwordx4 v[20:23], v4, s[4:5]
	s_add_u32 s4, s4, s6
	s_addc_u32 s5, s5, 0
	global_load_dwordx4 v[24:27], v4, s[4:5]
	s_add_u32 s4, s4, s6
	s_addc_u32 s5, s5, 0
	global_load_dwordx4 v[28:31], v4, s[4:5]
	s_add_u32 s4, s4, s6
	s_addc_u32 s5, s5, 0
	global_load_dwordx4 v[32:35], v4, s[4:5]
	s_add_u32 s4, s4, s6
	s_addc_u32 s5, s5, 0
	global_load_dwordx4 v[36:39], v4, s[4:5]
	s_add_u32 s4, s4, s6
	s_addc_u32 s5, s5, 0
	global_load_dwordx4 v[40:43], v4, s[4:5]
	s_add_u32 s4, s4, s6
	s_addc_u32 s5, s5, 0
	global_load_dwordx4 v[44:47], v4, s[4:5]
	s_cmp_lt_u32 s2, 1280
	s_cbranch_scc0 .Ltp02_c1
	s_mov_b32 s15, s2
	s_mul_hi_u32 s16, s15, 0x6666667
	s_mul_i32 s17, s16, 40
	s_sub_u32 s17, s15, s17
	v_readlane_b32 s4, v249, 24
	v_readlane_b32 s5, v249, 25
	s_mov_b32 s6, 0x2800
	s_mul_i32 s18, s16, 0x50000
	s_lshl_b32 s15, s17, 8
	s_add_u32 s18, s18, s15
	s_add_u32 s4, s4, s18
	s_addc_u32 s5, s5, 0
	s_branch .Ltp02_end
.Ltp02_c1:
	s_cmp_lt_u32 s2, 1792
	s_cbranch_scc0 .Ltp02_c2
	s_sub_u32 s15, s2, 0x500
	s_lshr_b32 s16, s15, 4
	s_and_b32 s17, s15, 15
	v_readlane_b32 s4, v248, 1
	v_readlane_b32 s5, v248, 2
	s_mov_b32 s6, 0x1000
	s_mul_i32 s18, s16, 0x20000
	s_lshl_b32 s15, s17, 8
	s_add_u32 s18, s18, s15
	s_add_u32 s4, s4, s18
	s_addc_u32 s5, s5, 0
	s_branch .Ltp02_end
.Ltp02_c2:
	s_cmp_lt_u32 s2, 1920
	s_cbranch_scc0 .Ltp02_c3
	s_sub_u32 s15, s2, 0x700
	s_lshr_b32 s16, s15, 4
	s_and_b32 s17, s15, 15
	v_readlane_b32 s4, v249, 55
	v_readlane_b32 s5, v249, 56
	s_mov_b32 s6, 0x1000
	s_mul_i32 s18, s16, 0x20000
	s_lshl_b32 s15, s17, 8
	s_add_u32 s18, s18, s15
	s_add_u32 s4, s4, s18
	s_addc_u32 s5, s5, 0
	s_branch .Ltp02_end
.Ltp02_c3:
	s_cmp_lt_u32 s2, 1936
	s_cbranch_scc0 .Ltp02_c4
	s_sub_u32 s15, s2, 0x780
	s_lshr_b32 s19, s15, 1
	s_bfe_u32 s16, s15, 0x10000
	s_mov_b32 s17, 0
	v_readlane_b32 s4, v249, 30
	v_readlane_b32 s5, v249, 31
	s_mov_b32 s6, 0x100
	s_mul_i32 s18, s16, 0x2000
	s_lshl_b32 s15, s17, 8
	s_add_u32 s18, s18, s15
	s_mul_i32 s15, s19, 0x4000
	s_add_u32 s18, s18, s15
	s_add_u32 s4, s4, s18
	s_addc_u32 s5, s5, 0
	s_branch .Ltp02_end
.Ltp02_c4:
	s_cmp_lt_u32 s2, 1952
	s_cbranch_scc0 .Ltp02_c5
	s_sub_u32 s15, s2, 0x790
	s_lshr_b32 s19, s15, 1
	s_bfe_u32 s16, s15, 0x10000
	s_mov_b32 s17, 0
	v_readlane_b32 s4, v249, 34
	v_readlane_b32 s5, v249, 35
	s_mov_b32 s6, 0x100
	s_mul_i32 s18, s16, 0x2000
	s_lshl_b32 s15, s17, 8
	s_add_u32 s18, s18, s15
	s_mul_i32 s15, s19, 0x4000
	s_add_u32 s18, s18, s15
	s_add_u32 s4, s4, s18
	s_addc_u32 s5, s5, 0
	s_branch .Ltp02_end
.Ltp02_c5:
	s_sub_u32 s15, s2, 0x7a0
	s_lshr_b32 s19, s15, 7
	s_bfe_u32 s16, s15, 0x40003
	s_and_b32 s17, s15, 7
	v_readlane_b32 s4, v249, 16
	v_readlane_b32 s5, v249, 17
	s_mov_b32 s6, 0x800
	s_mul_i32 s18, s16, 0x10000
	s_lshl_b32 s15, s17, 8
	s_add_u32 s18, s18, s15
	s_mul_i32 s15, s19, 0x100000
	s_add_u32 s18, s18, s15
	s_add_u32 s4, s4, s18
	s_addc_u32 s5, s5, 0
.Ltp02_end:
	s_lshl_b32 s7, s6, 3
	s_nop 0
	v_mad_u32_u24 v4, v1, s7, v0
	s_nop 3
	global_load_dwordx4 v[56:59], v4, s[4:5]
	s_add_u32 s4, s4, s6
	s_addc_u32 s5, s5, 0
	global_load_dwordx4 v[60:63], v4, s[4:5]
	s_add_u32 s4, s4, s6
	s_addc_u32 s5, s5, 0
	global_load_dwordx4 v[64:67], v4, s[4:5]
	s_add_u32 s4, s4, s6
	s_addc_u32 s5, s5, 0
	global_load_dwordx4 v[68:71], v4, s[4:5]
	s_add_u32 s4, s4, s6
	s_addc_u32 s5, s5, 0
	global_load_dwordx4 v[72:75], v4, s[4:5]
	s_add_u32 s4, s4, s6
	s_addc_u32 s5, s5, 0
	global_load_dwordx4 v[76:79], v4, s[4:5]
	s_add_u32 s4, s4, s6
	s_addc_u32 s5, s5, 0
	global_load_dwordx4 v[80:83], v4, s[4:5]
	s_add_u32 s4, s4, s6
	s_addc_u32 s5, s5, 0
	global_load_dwordx4 v[84:87], v4, s[4:5]
	s_cmp_lt_u32 s3, 1280
	s_cbranch_scc0 .Ltp03_c1
	s_mov_b32 s15, s3
	s_mul_hi_u32 s16, s15, 0x6666667
	s_mul_i32 s17, s16, 40
	s_sub_u32 s17, s15, s17
	v_readlane_b32 s4, v249, 24
	v_readlane_b32 s5, v249, 25
	s_mov_b32 s6, 0x2800
	s_mul_i32 s18, s16, 0x50000
	s_lshl_b32 s15, s17, 8
	s_add_u32 s18, s18, s15
	s_add_u32 s4, s4, s18
	s_addc_u32 s5, s5, 0
	s_branch .Ltp03_end
.Ltp03_c1:
	s_cmp_lt_u32 s3, 1792
	s_cbranch_scc0 .Ltp03_c2
	s_sub_u32 s15, s3, 0x500
	s_lshr_b32 s16, s15, 4
	s_and_b32 s17, s15, 15
	v_readlane_b32 s4, v248, 1
	v_readlane_b32 s5, v248, 2
	s_mov_b32 s6, 0x1000
	s_mul_i32 s18, s16, 0x20000
	s_lshl_b32 s15, s17, 8
	s_add_u32 s18, s18, s15
	s_add_u32 s4, s4, s18
	s_addc_u32 s5, s5, 0
	s_branch .Ltp03_end
.Ltp03_c2:
	s_cmp_lt_u32 s3, 1920
	s_cbranch_scc0 .Ltp03_c3
	s_sub_u32 s15, s3, 0x700
	s_lshr_b32 s16, s15, 4
	s_and_b32 s17, s15, 15
	v_readlane_b32 s4, v249, 55
	v_readlane_b32 s5, v249, 56
	s_mov_b32 s6, 0x1000
	s_mul_i32 s18, s16, 0x20000
	s_lshl_b32 s15, s17, 8
	s_add_u32 s18, s18, s15
	s_add_u32 s4, s4, s18
	s_addc_u32 s5, s5, 0
	s_branch .Ltp03_end
.Ltp03_c3:
	s_cmp_lt_u32 s3, 1936
	s_cbranch_scc0 .Ltp03_c4
	s_sub_u32 s15, s3, 0x780
	s_lshr_b32 s19, s15, 1
	s_bfe_u32 s16, s15, 0x10000
	s_mov_b32 s17, 0
	v_readlane_b32 s4, v249, 30
	v_readlane_b32 s5, v249, 31
	s_mov_b32 s6, 0x100
	s_mul_i32 s18, s16, 0x2000
	s_lshl_b32 s15, s17, 8
	s_add_u32 s18, s18, s15
	s_mul_i32 s15, s19, 0x4000
	s_add_u32 s18, s18, s15
	s_add_u32 s4, s4, s18
	s_addc_u32 s5, s5, 0
	s_branch .Ltp03_end
.Ltp03_c4:
	s_cmp_lt_u32 s3, 1952
	s_cbranch_scc0 .Ltp03_c5
	s_sub_u32 s15, s3, 0x790
	s_lshr_b32 s19, s15, 1
	s_bfe_u32 s16, s15, 0x10000
	s_mov_b32 s17, 0
	v_readlane_b32 s4, v249, 34
	v_readlane_b32 s5, v249, 35
	s_mov_b32 s6, 0x100
	s_mul_i32 s18, s16, 0x2000
	s_lshl_b32 s15, s17, 8
	s_add_u32 s18, s18, s15
	s_mul_i32 s15, s19, 0x4000
	s_add_u32 s18, s18, s15
	s_add_u32 s4, s4, s18
	s_addc_u32 s5, s5, 0
	s_branch .Ltp03_end
.Ltp03_c5:
	s_sub_u32 s15, s3, 0x7a0
	s_lshr_b32 s19, s15, 7
	s_bfe_u32 s16, s15, 0x40003
	s_and_b32 s17, s15, 7
	v_readlane_b32 s4, v249, 16
	v_readlane_b32 s5, v249, 17
	s_mov_b32 s6, 0x800
	s_mul_i32 s18, s16, 0x10000
	s_lshl_b32 s15, s17, 8
	s_add_u32 s18, s18, s15
	s_mul_i32 s15, s19, 0x100000
	s_add_u32 s18, s18, s15
	s_add_u32 s4, s4, s18
	s_addc_u32 s5, s5, 0
.Ltp03_end:
	s_lshl_b32 s7, s6, 3
	s_nop 0
	v_mad_u32_u24 v4, v1, s7, v0
	s_nop 3
	global_load_dwordx4 v[96:99], v4, s[4:5]
	s_add_u32 s4, s4, s6
	s_addc_u32 s5, s5, 0
	global_load_dwordx4 v[100:103], v4, s[4:5]
	s_add_u32 s4, s4, s6
	s_addc_u32 s5, s5, 0
	global_load_dwordx4 v[104:107], v4, s[4:5]
	s_add_u32 s4, s4, s6
	s_addc_u32 s5, s5, 0
	global_load_dwordx4 v[108:111], v4, s[4:5]
	s_add_u32 s4, s4, s6
	s_addc_u32 s5, s5, 0
	global_load_dwordx4 v[112:115], v4, s[4:5]
	s_add_u32 s4, s4, s6
	s_addc_u32 s5, s5, 0
	global_load_dwordx4 v[116:119], v4, s[4:5]
	s_add_u32 s4, s4, s6
	s_addc_u32 s5, s5, 0
	global_load_dwordx4 v[120:123], v4, s[4:5]
	s_add_u32 s4, s4, s6
	s_addc_u32 s5, s5, 0
	global_load_dwordx4 v[124:127], v4, s[4:5]
	s_waitcnt vmcnt(16)
	s_cmp_lt_u32 s0, 1280
	s_cbranch_scc0 .Ltp04_c1
	s_mov_b32 s15, s0
	s_mul_hi_u32 s16, s15, 0x6666667
	s_mul_i32 s17, s16, 40
	s_sub_u32 s17, s15, s17
	s_mov_b32 s10, 0x800
	s_lshl_b32 s15, s17, 6
	s_mul_i32 s15, s15, s10
	s_lshl_b32 s18, s16, 6
	s_add_u32 s15, s15, s18
	s_add_u32 s8, s24, s15
	s_addc_u32 s9, s25, 0
	s_branch .Ltp04_end
.Ltp04_c1:
	s_cmp_lt_u32 s0, 1792
	s_cbranch_scc0 .Ltp04_c2
	s_sub_u32 s15, s0, 0x500
	s_lshr_b32 s16, s15, 4
	s_and_b32 s17, s15, 15
	s_mov_b32 s10, 0x800
	s_lshl_b32 s15, s17, 6
	s_mul_i32 s15, s15, s10
	s_lshl_b32 s18, s16, 6
	s_add_u32 s15, s15, s18
	s_add_u32 s15, s15, 0x500000
	s_add_u32 s8, s24, s15
	s_addc_u32 s9, s25, 0
	s_branch .Ltp04_end
.Ltp04_c2:
	s_cmp_lt_u32 s0, 1920
	s_cbranch_scc0 .Ltp04_c3
	s_sub_u32 s15, s0, 0x700
	s_lshr_b32 s16, s15, 4
	s_and_b32 s17, s15, 15
	s_mov_b32 s10, 0x200
	s_lshl_b32 s15, s17, 6
	s_mul_i32 s15, s15, s10
	s_lshl_b32 s18, s16, 6
	s_add_u32 s15, s15, s18
	s_add_u32 s15, s15, 0x1980000
	s_add_u32 s8, s24, s15
	s_addc_u32 s9, s25, 0
	s_branch .Ltp04_end
.Ltp04_c3:
	s_cmp_lt_u32 s0, 1936
	s_cbranch_scc0 .Ltp04_c4
	s_sub_u32 s15, s0, 0x780
	s_lshr_b32 s19, s15, 1
	s_bfe_u32 s16, s15, 0x10000
	s_mov_b32 s17, 0
	s_mov_b32 s10, 0x80
	s_lshl_b32 s15, s17, 6
	s_mul_i32 s15, s15, s10
	s_lshl_b32 s18, s16, 6
	s_add_u32 s15, s15, s18
	s_mul_i32 s18, s19, 0x2000
	s_add_u32 s15, s15, s18
	s_add_u32 s15, s15, 0x1a00000
	s_add_u32 s8, s24, s15
	s_addc_u32 s9, s25, 0
	s_branch .Ltp04_end
.Ltp04_c4:
	s_cmp_lt_u32 s0, 1952
	s_cbranch_scc0 .Ltp04_c5
	s_sub_u32 s15, s0, 0x790
	s_lshr_b32 s19, s15, 1
	s_bfe_u32 s16, s15, 0x10000
	s_mov_b32 s17, 0
	s_mov_b32 s10, 0x80
	s_lshl_b32 s15, s17, 6
	s_mul_i32 s15, s15, s10
	s_lshl_b32 s18, s16, 6
	s_add_u32 s15, s15, s18
	s_mul_i32 s18, s19, 0x2000
	s_add_u32 s15, s15, s18
	s_add_u32 s15, s15, 0x1a10000
	s_add_u32 s8, s24, s15
	s_addc_u32 s9, s25, 0
	s_branch .Ltp04_end
.Ltp04_c5:
	s_sub_u32 s15, s0, 0x7a0
	s_lshr_b32 s19, s15, 7
	s_bfe_u32 s16, s15, 0x40003
	s_and_b32 s17, s15, 7
	s_mov_b32 s10, 0x400
	s_lshl_b32 s15, s17, 6
	s_mul_i32 s15, s15, s10
	s_lshl_b32 s18, s16, 6
	s_add_u32 s15, s15, s18
	s_mul_i32 s18, s19, 0x80000
	s_add_u32 s15, s15, s18
	s_add_u32 s15, s15, 0x149c5000
	s_add_u32 s8, s24, s15
	s_addc_u32 s9, s25, 0
.Ltp04_end:
	v_mad_u32_u24 v5, v2, s10, v6
	v_cvt_pk_bf16_f32 v136, v16, v20
	v_cvt_pk_bf16_f32 v137, v24, v28
	v_cvt_pk_bf16_f32 v138, v32, v36
	v_cvt_pk_bf16_f32 v139, v40, v44
	v_cvt_pk_bf16_f32 v140, v17, v21
	v_cvt_pk_bf16_f32 v141, v25, v29
	v_cvt_pk_bf16_f32 v142, v33, v37
	v_cvt_pk_bf16_f32 v143, v41, v45
	v_cvt_pk_bf16_f32 v144, v18, v22
	v_cvt_pk_bf16_f32 v145, v26, v30
	v_cvt_pk_bf16_f32 v146, v34, v38
	v_cvt_pk_bf16_f32 v147, v42, v46
	v_cvt_pk_bf16_f32 v148, v19, v23
	v_cvt_pk_bf16_f32 v149, v27, v31
	v_cvt_pk_bf16_f32 v150, v35, v39
	v_cvt_pk_bf16_f32 v151, v43, v47
	global_store_dwordx4 v5, v[136:139], s[8:9]
	s_add_u32 s8, s8, s10
	s_addc_u32 s9, s9, 0
	global_store_dwordx4 v5, v[140:143], s[8:9]
	s_add_u32 s8, s8, s10
	s_addc_u32 s9, s9, 0
	global_store_dwordx4 v5, v[144:147], s[8:9]
	s_add_u32 s8, s8, s10
	s_addc_u32 s9, s9, 0
	global_store_dwordx4 v5, v[148:151], s[8:9]
	s_add_u32 s11, s0, s1
	s_cmp_lt_u32 s11, 6048
	s_cbranch_scc0 .Ltp0_done
	s_waitcnt vmcnt(12)
	s_cmp_lt_u32 s2, 1280
	s_cbranch_scc0 .Ltp05_c1
	s_mov_b32 s15, s2
	s_mul_hi_u32 s16, s15, 0x6666667
	s_mul_i32 s17, s16, 40
	s_sub_u32 s17, s15, s17
	s_mov_b32 s10, 0x800
	s_lshl_b32 s15, s17, 6
	s_mul_i32 s15, s15, s10
	s_lshl_b32 s18, s16, 6
	s_add_u32 s15, s15, s18
	s_add_u32 s8, s24, s15
	s_addc_u32 s9, s25, 0
	s_branch .Ltp05_end
.Ltp05_c1:
	s_cmp_lt_u32 s2, 1792
	s_cbranch_scc0 .Ltp05_c2
	s_sub_u32 s15, s2, 0x500
	s_lshr_b32 s16, s15, 4
	s_and_b32 s17, s15, 15
	s_mov_b32 s10, 0x800
	s_lshl_b32 s15, s17, 6
	s_mul_i32 s15, s15, s10
	s_lshl_b32 s18, s16, 6
	s_add_u32 s15, s15, s18
	s_add_u32 s15, s15, 0x500000
	s_add_u32 s8, s24, s15
	s_addc_u32 s9, s25, 0
	s_branch .Ltp05_end
.Ltp05_c2:
	s_cmp_lt_u32 s2, 1920
	s_cbranch_scc0 .Ltp05_c3
	s_sub_u32 s15, s2, 0x700
	s_lshr_b32 s16, s15, 4
	s_and_b32 s17, s15, 15
	s_mov_b32 s10, 0x200
	s_lshl_b32 s15, s17, 6
	s_mul_i32 s15, s15, s10
	s_lshl_b32 s18, s16, 6
	s_add_u32 s15, s15, s18
	s_add_u32 s15, s15, 0x1980000
	s_add_u32 s8, s24, s15
	s_addc_u32 s9, s25, 0
	s_branch .Ltp05_end
.Ltp05_c3:
	s_cmp_lt_u32 s2, 1936
	s_cbranch_scc0 .Ltp05_c4
	s_sub_u32 s15, s2, 0x780
	s_lshr_b32 s19, s15, 1
	s_bfe_u32 s16, s15, 0x10000
	s_mov_b32 s17, 0
	s_mov_b32 s10, 0x80
	s_lshl_b32 s15, s17, 6
	s_mul_i32 s15, s15, s10
	s_lshl_b32 s18, s16, 6
	s_add_u32 s15, s15, s18
	s_mul_i32 s18, s19, 0x2000
	s_add_u32 s15, s15, s18
	s_add_u32 s15, s15, 0x1a00000
	s_add_u32 s8, s24, s15
	s_addc_u32 s9, s25, 0
	s_branch .Ltp05_end
.Ltp05_c4:
	s_cmp_lt_u32 s2, 1952
	s_cbranch_scc0 .Ltp05_c5
	s_sub_u32 s15, s2, 0x790
	s_lshr_b32 s19, s15, 1
	s_bfe_u32 s16, s15, 0x10000
	s_mov_b32 s17, 0
	s_mov_b32 s10, 0x80
	s_lshl_b32 s15, s17, 6
	s_mul_i32 s15, s15, s10
	s_lshl_b32 s18, s16, 6
	s_add_u32 s15, s15, s18
	s_mul_i32 s18, s19, 0x2000
	s_add_u32 s15, s15, s18
	s_add_u32 s15, s15, 0x1a10000
	s_add_u32 s8, s24, s15
	s_addc_u32 s9, s25, 0
	s_branch .Ltp05_end
.Ltp05_c5:
	s_sub_u32 s15, s2, 0x7a0
	s_lshr_b32 s19, s15, 7
	s_bfe_u32 s16, s15, 0x40003
	s_and_b32 s17, s15, 7
	s_mov_b32 s10, 0x400
	s_lshl_b32 s15, s17, 6
	s_mul_i32 s15, s15, s10
	s_lshl_b32 s18, s16, 6
	s_add_u32 s15, s15, s18
	s_mul_i32 s18, s19, 0x80000
	s_add_u32 s15, s15, s18
	s_add_u32 s15, s15, 0x149c5000
	s_add_u32 s8, s24, s15
	s_addc_u32 s9, s25, 0
.Ltp05_end:
	v_mad_u32_u24 v5, v2, s10, v6
	v_cvt_pk_bf16_f32 v136, v56, v60
	v_cvt_pk_bf16_f32 v137, v64, v68
	v_cvt_pk_bf16_f32 v138, v72, v76
	v_cvt_pk_bf16_f32 v139, v80, v84
	v_cvt_pk_bf16_f32 v140, v57, v61
	v_cvt_pk_bf16_f32 v141, v65, v69
	v_cvt_pk_bf16_f32 v142, v73, v77
	v_cvt_pk_bf16_f32 v143, v81, v85
	v_cvt_pk_bf16_f32 v144, v58, v62
	v_cvt_pk_bf16_f32 v145, v66, v70
	v_cvt_pk_bf16_f32 v146, v74, v78
	v_cvt_pk_bf16_f32 v147, v82, v86
	v_cvt_pk_bf16_f32 v148, v59, v63
	v_cvt_pk_bf16_f32 v149, v67, v71
	v_cvt_pk_bf16_f32 v150, v75, v79
	v_cvt_pk_bf16_f32 v151, v83, v87
	global_store_dwordx4 v5, v[136:139], s[8:9]
	s_add_u32 s8, s8, s10
	s_addc_u32 s9, s9, 0
	global_store_dwordx4 v5, v[140:143], s[8:9]
	s_add_u32 s8, s8, s10
	s_addc_u32 s9, s9, 0
	global_store_dwordx4 v5, v[144:147], s[8:9]
	s_add_u32 s8, s8, s10
	s_addc_u32 s9, s9, 0
	global_store_dwordx4 v5, v[148:151], s[8:9]
	s_add_u32 s11, s11, s1
	s_cmp_lt_u32 s11, 6048
	s_cbranch_scc0 .Ltp0_done
	s_waitcnt vmcnt(8)
	s_cmp_lt_u32 s3, 1280
	s_cbranch_scc0 .Ltp06_c1
	s_mov_b32 s15, s3
	s_mul_hi_u32 s16, s15, 0x6666667
	s_mul_i32 s17, s16, 40
	s_sub_u32 s17, s15, s17
	s_mov_b32 s10, 0x800
	s_lshl_b32 s15, s17, 6
	s_mul_i32 s15, s15, s10
	s_lshl_b32 s18, s16, 6
	s_add_u32 s15, s15, s18
	s_add_u32 s8, s24, s15
	s_addc_u32 s9, s25, 0
	s_branch .Ltp06_end
.Ltp06_c1:
	s_cmp_lt_u32 s3, 1792
	s_cbranch_scc0 .Ltp06_c2
	s_sub_u32 s15, s3, 0x500
	s_lshr_b32 s16, s15, 4
	s_and_b32 s17, s15, 15
	s_mov_b32 s10, 0x800
	s_lshl_b32 s15, s17, 6
	s_mul_i32 s15, s15, s10
	s_lshl_b32 s18, s16, 6
	s_add_u32 s15, s15, s18
	s_add_u32 s15, s15, 0x500000
	s_add_u32 s8, s24, s15
	s_addc_u32 s9, s25, 0
	s_branch .Ltp06_end
.Ltp06_c2:
	s_cmp_lt_u32 s3, 1920
	s_cbranch_scc0 .Ltp06_c3
	s_sub_u32 s15, s3, 0x700
	s_lshr_b32 s16, s15, 4
	s_and_b32 s17, s15, 15
	s_mov_b32 s10, 0x200
	s_lshl_b32 s15, s17, 6
	s_mul_i32 s15, s15, s10
	s_lshl_b32 s18, s16, 6
	s_add_u32 s15, s15, s18
	s_add_u32 s15, s15, 0x1980000
	s_add_u32 s8, s24, s15
	s_addc_u32 s9, s25, 0
	s_branch .Ltp06_end
.Ltp06_c3:
	s_cmp_lt_u32 s3, 1936
	s_cbranch_scc0 .Ltp06_c4
	s_sub_u32 s15, s3, 0x780
	s_lshr_b32 s19, s15, 1
	s_bfe_u32 s16, s15, 0x10000
	s_mov_b32 s17, 0
	s_mov_b32 s10, 0x80
	s_lshl_b32 s15, s17, 6
	s_mul_i32 s15, s15, s10
	s_lshl_b32 s18, s16, 6
	s_add_u32 s15, s15, s18
	s_mul_i32 s18, s19, 0x2000
	s_add_u32 s15, s15, s18
	s_add_u32 s15, s15, 0x1a00000
	s_add_u32 s8, s24, s15
	s_addc_u32 s9, s25, 0
	s_branch .Ltp06_end
.Ltp06_c4:
	s_cmp_lt_u32 s3, 1952
	s_cbranch_scc0 .Ltp06_c5
	s_sub_u32 s15, s3, 0x790
	s_lshr_b32 s19, s15, 1
	s_bfe_u32 s16, s15, 0x10000
	s_mov_b32 s17, 0
	s_mov_b32 s10, 0x80
	s_lshl_b32 s15, s17, 6
	s_mul_i32 s15, s15, s10
	s_lshl_b32 s18, s16, 6
	s_add_u32 s15, s15, s18
	s_mul_i32 s18, s19, 0x2000
	s_add_u32 s15, s15, s18
	s_add_u32 s15, s15, 0x1a10000
	s_add_u32 s8, s24, s15
	s_addc_u32 s9, s25, 0
	s_branch .Ltp06_end
.Ltp06_c5:
	s_sub_u32 s15, s3, 0x7a0
	s_lshr_b32 s19, s15, 7
	s_bfe_u32 s16, s15, 0x40003
	s_and_b32 s17, s15, 7
	s_mov_b32 s10, 0x400
	s_lshl_b32 s15, s17, 6
	s_mul_i32 s15, s15, s10
	s_lshl_b32 s18, s16, 6
	s_add_u32 s15, s15, s18
	s_mul_i32 s18, s19, 0x80000
	s_add_u32 s15, s15, s18
	s_add_u32 s15, s15, 0x149c5000
	s_add_u32 s8, s24, s15
	s_addc_u32 s9, s25, 0
.Ltp06_end:
	v_mad_u32_u24 v5, v2, s10, v6
	v_cvt_pk_bf16_f32 v136, v96, v100
	v_cvt_pk_bf16_f32 v137, v104, v108
	v_cvt_pk_bf16_f32 v138, v112, v116
	v_cvt_pk_bf16_f32 v139, v120, v124
	v_cvt_pk_bf16_f32 v140, v97, v101
	v_cvt_pk_bf16_f32 v141, v105, v109
	v_cvt_pk_bf16_f32 v142, v113, v117
	v_cvt_pk_bf16_f32 v143, v121, v125
	v_cvt_pk_bf16_f32 v144, v98, v102
	v_cvt_pk_bf16_f32 v145, v106, v110
	v_cvt_pk_bf16_f32 v146, v114, v118
	v_cvt_pk_bf16_f32 v147, v122, v126
	v_cvt_pk_bf16_f32 v148, v99, v103
	v_cvt_pk_bf16_f32 v149, v107, v111
	v_cvt_pk_bf16_f32 v150, v115, v119
	v_cvt_pk_bf16_f32 v151, v123, v127
	global_store_dwordx4 v5, v[136:139], s[8:9]
	s_add_u32 s8, s8, s10
	s_addc_u32 s9, s9, 0
	global_store_dwordx4 v5, v[140:143], s[8:9]
	s_add_u32 s8, s8, s10
	s_addc_u32 s9, s9, 0
	global_store_dwordx4 v5, v[144:147], s[8:9]
	s_add_u32 s8, s8, s10
	s_addc_u32 s9, s9, 0
	global_store_dwordx4 v5, v[148:151], s[8:9]
	s_add_u32 s0, s11, s1
	s_branch .Ltp0_loop
.Ltp0_done:
	v_readlane_b32 s0, v251, 0
	v_readlane_b32 s1, v251, 1
	v_readlane_b32 s2, v251, 2
	v_readlane_b32 s3, v251, 3
	v_readlane_b32 s4, v251, 4
	v_readlane_b32 s5, v251, 5
	v_readlane_b32 s6, v251, 6
	v_readlane_b32 s7, v251, 7
	v_readlane_b32 s8, v251, 8
	v_readlane_b32 s9, v251, 9
	v_readlane_b32 s10, v251, 10
	v_readlane_b32 s11, v251, 11
	v_readlane_b32 s12, v251, 12
	v_readlane_b32 s13, v251, 13
	v_readlane_b32 s14, v251, 14
	v_readlane_b32 s15, v251, 15
	v_readlane_b32 s16, v251, 16
	v_readlane_b32 s17, v251, 17
	v_readlane_b32 s18, v251, 18
	v_readlane_b32 s19, v251, 19
	s_nop 1
	v_mov_b32_e32 v0, v184

.Ltp4_loop:
	s_cmp_lt_u32 s0, 4736
	s_cbranch_scc0 .Ltp4_done
	s_add_u32 s2, s0, s1
	s_cmp_lt_u32 s2, 4736
	s_cselect_b32 s2, s2, s0
	s_add_u32 s3, s0, s1
	s_add_u32 s3, s3, s1
	s_cmp_lt_u32 s3, 4736
	s_cselect_b32 s3, s3, s0
	s_cmp_lt_u32 s0, 1408
	s_cbranch_scc0 .Ltp41_c1
	s_mov_b32 s15, s0
	s_mul_hi_u32 s16, s15, 0x5d1745e
	s_mul_i32 s17, s16, 44
	s_sub_u32 s17, s15, s17
	v_readlane_b32 s4, v248, 5
	v_readlane_b32 s5, v248, 6
	v_readlane_b32 s12, v248, 3
	v_readlane_b32 s13, v248, 4
	s_mov_b32 s6, 0x2c00
	s_mul_i32 s18, s16, 0x58000
	s_lshl_b32 s15, s17, 8
	s_add_u32 s18, s18, s15
	s_add_u32 s4, s4, s18
	s_addc_u32 s5, s5, 0
	s_lshl_b32 s15, s16, 7
	s_add_u32 s12, s12, s15
	s_addc_u32 s13, s13, 0
	s_branch .Ltp41_end
.Ltp41_c1:
	s_cmp_lt_u32 s0, 2816
	s_cbranch_scc0 .Ltp41_c2
	s_sub_u32 s15, s0, 0x580
	s_mul_hi_u32 s16, s15, 0x5d1745e
	s_mul_i32 s17, s16, 44
	s_sub_u32 s17, s15, s17
	v_readlane_b32 s4, v248, 7
	v_readlane_b32 s5, v248, 8
	v_readlane_b32 s12, v248, 3
	v_readlane_b32 s13, v248, 4
	s_mov_b32 s6, 0x2c00
	s_mul_i32 s18, s16, 0x58000
	s_lshl_b32 s15, s17, 8
	s_add_u32 s18, s18, s15
	s_add_u32 s4, s4, s18
	s_addc_u32 s5, s5, 0
	s_lshl_b32 s15, s16, 7
	s_add_u32 s12, s12, s15
	s_addc_u32 s13, s13, 0
	s_branch .Ltp41_end
.Ltp41_c2:
	s_cmp_lt_u32 s0, 4224
	s_cbranch_scc0 .Ltp41_c3
	s_sub_u32 s15, s0, 0xb00
	s_lshr_b32 s16, s15, 4
	s_and_b32 s17, s15, 15
	v_readlane_b32 s4, v249, 49
	v_readlane_b32 s5, v249, 50
	v_readlane_b32 s12, v248, 3
	v_readlane_b32 s13, v248, 4
	s_mov_b32 s6, 0x1000
	s_mul_i32 s18, s16, 0x20000
	s_lshl_b32 s15, s17, 8
	s_add_u32 s18, s18, s15
	s_add_u32 s4, s4, s18
	s_addc_u32 s5, s5, 0
	s_branch .Ltp41_end
.Ltp41_c3:
	s_sub_u32 s15, s0, 0x1080
	s_lshr_b32 s16, s15, 4
	s_and_b32 s17, s15, 15
	v_readlane_b32 s4, v249, 53
	v_readlane_b32 s5, v249, 54
	v_readlane_b32 s12, v249, 51
	v_readlane_b32 s13, v249, 52
	s_mov_b32 s6, 0x1000
	s_mul_i32 s18, s16, 0x20000
	s_lshl_b32 s15, s17, 8
	s_add_u32 s18, s18, s15
	s_add_u32 s4, s4, s18
	s_addc_u32 s5, s5, 0
	s_lshl_b32 s15, s16, 7
	s_add_u32 s12, s12, s15
	s_addc_u32 s13, s13, 0
.Ltp41_end:
	s_lshl_b32 s7, s6, 3
	s_nop 0
	v_mad_u32_u24 v4, v1, s7, v0
	s_nop 3
	global_load_dwordx4 v[16:19], v4, s[4:5]
	s_add_u32 s4, s4, s6
	s_addc_u32 s5, s5, 0
	global_load_dwordx4 v[20:23], v4, s[4:5]
	s_add_u32 s4, s4, s6
	s_addc_u32 s5, s5, 0
	global_load_dwordx4 v[24:27], v4, s[4:5]
	s_add_u32 s4, s4, s6
	s_addc_u32 s5, s5, 0
	global_load_dwordx4 v[28:31], v4, s[4:5]
	s_add_u32 s4, s4, s6
	s_addc_u32 s5, s5, 0
	global_load_dwordx4 v[32:35], v4, s[4:5]
	s_add_u32 s4, s4, s6
	s_addc_u32 s5, s5, 0
	global_load_dwordx4 v[36:39], v4, s[4:5]
	s_add_u32 s4, s4, s6
	s_addc_u32 s5, s5, 0
	global_load_dwordx4 v[40:43], v4, s[4:5]
	s_add_u32 s4, s4, s6
	s_addc_u32 s5, s5, 0
	global_load_dwordx4 v[44:47], v4, s[4:5]
	global_load_dwordx4 v[48:51], v3, s[12:13]
	global_load_dwordx4 v[52:55], v3, s[12:13] offset:16
	s_cmp_lt_u32 s2, 1408
	s_cbranch_scc0 .Ltp42_c1
	s_mov_b32 s15, s2
	s_mul_hi_u32 s16, s15, 0x5d1745e
	s_mul_i32 s17, s16, 44
	s_sub_u32 s17, s15, s17
	v_readlane_b32 s4, v248, 5
	v_readlane_b32 s5, v248, 6
	v_readlane_b32 s12, v248, 3
	v_readlane_b32 s13, v248, 4
	s_mov_b32 s6, 0x2c00
	s_mul_i32 s18, s16, 0x58000
	s_lshl_b32 s15, s17, 8
	s_add_u32 s18, s18, s15
	s_add_u32 s4, s4, s18
	s_addc_u32 s5, s5, 0
	s_lshl_b32 s15, s16, 7
	s_add_u32 s12, s12, s15
	s_addc_u32 s13, s13, 0
	s_branch .Ltp42_end
.Ltp42_c1:
	s_cmp_lt_u32 s2, 2816
	s_cbranch_scc0 .Ltp42_c2
	s_sub_u32 s15, s2, 0x580
	s_mul_hi_u32 s16, s15, 0x5d1745e
	s_mul_i32 s17, s16, 44
	s_sub_u32 s17, s15, s17
	v_readlane_b32 s4, v248, 7
	v_readlane_b32 s5, v248, 8
	v_readlane_b32 s12, v248, 3
	v_readlane_b32 s13, v248, 4
	s_mov_b32 s6, 0x2c00
	s_mul_i32 s18, s16, 0x58000
	s_lshl_b32 s15, s17, 8
	s_add_u32 s18, s18, s15
	s_add_u32 s4, s4, s18
	s_addc_u32 s5, s5, 0
	s_lshl_b32 s15, s16, 7
	s_add_u32 s12, s12, s15
	s_addc_u32 s13, s13, 0
	s_branch .Ltp42_end
.Ltp42_c2:
	s_cmp_lt_u32 s2, 4224
	s_cbranch_scc0 .Ltp42_c3
	s_sub_u32 s15, s2, 0xb00
	s_lshr_b32 s16, s15, 4
	s_and_b32 s17, s15, 15
	v_readlane_b32 s4, v249, 49
	v_readlane_b32 s5, v249, 50
	v_readlane_b32 s12, v248, 3
	v_readlane_b32 s13, v248, 4
	s_mov_b32 s6, 0x1000
	s_mul_i32 s18, s16, 0x20000
	s_lshl_b32 s15, s17, 8
	s_add_u32 s18, s18, s15
	s_add_u32 s4, s4, s18
	s_addc_u32 s5, s5, 0
	s_branch .Ltp42_end
.Ltp42_c3:
	s_sub_u32 s15, s2, 0x1080
	s_lshr_b32 s16, s15, 4
	s_and_b32 s17, s15, 15
	v_readlane_b32 s4, v249, 53
	v_readlane_b32 s5, v249, 54
	v_readlane_b32 s12, v249, 51
	v_readlane_b32 s13, v249, 52
	s_mov_b32 s6, 0x1000
	s_mul_i32 s18, s16, 0x20000
	s_lshl_b32 s15, s17, 8
	s_add_u32 s18, s18, s15
	s_add_u32 s4, s4, s18
	s_addc_u32 s5, s5, 0
	s_lshl_b32 s15, s16, 7
	s_add_u32 s12, s12, s15
	s_addc_u32 s13, s13, 0
.Ltp42_end:
	s_lshl_b32 s7, s6, 3
	s_nop 0
	v_mad_u32_u24 v4, v1, s7, v0
	s_nop 3
	global_load_dwordx4 v[56:59], v4, s[4:5]
	s_add_u32 s4, s4, s6
	s_addc_u32 s5, s5, 0
	global_load_dwordx4 v[60:63], v4, s[4:5]
	s_add_u32 s4, s4, s6
	s_addc_u32 s5, s5, 0
	global_load_dwordx4 v[64:67], v4, s[4:5]
	s_add_u32 s4, s4, s6
	s_addc_u32 s5, s5, 0
	global_load_dwordx4 v[68:71], v4, s[4:5]
	s_add_u32 s4, s4, s6
	s_addc_u32 s5, s5, 0
	global_load_dwordx4 v[72:75], v4, s[4:5]
	s_add_u32 s4, s4, s6
	s_addc_u32 s5, s5, 0
	global_load_dwordx4 v[76:79], v4, s[4:5]
	s_add_u32 s4, s4, s6
	s_addc_u32 s5, s5, 0
	global_load_dwordx4 v[80:83], v4, s[4:5]
	s_add_u32 s4, s4, s6
	s_addc_u32 s5, s5, 0
	global_load_dwordx4 v[84:87], v4, s[4:5]
	global_load_dwordx4 v[88:91], v3, s[12:13]
	global_load_dwordx4 v[92:95], v3, s[12:13] offset:16
	s_cmp_lt_u32 s3, 1408
	s_cbranch_scc0 .Ltp43_c1
	s_mov_b32 s15, s3
	s_mul_hi_u32 s16, s15, 0x5d1745e
	s_mul_i32 s17, s16, 44
	s_sub_u32 s17, s15, s17
	v_readlane_b32 s4, v248, 5
	v_readlane_b32 s5, v248, 6
	v_readlane_b32 s12, v248, 3
	v_readlane_b32 s13, v248, 4
	s_mov_b32 s6, 0x2c00
	s_mul_i32 s18, s16, 0x58000
	s_lshl_b32 s15, s17, 8
	s_add_u32 s18, s18, s15
	s_add_u32 s4, s4, s18
	s_addc_u32 s5, s5, 0
	s_lshl_b32 s15, s16, 7
	s_add_u32 s12, s12, s15
	s_addc_u32 s13, s13, 0
	s_branch .Ltp43_end
.Ltp43_c1:
	s_cmp_lt_u32 s3, 2816
	s_cbranch_scc0 .Ltp43_c2
	s_sub_u32 s15, s3, 0x580
	s_mul_hi_u32 s16, s15, 0x5d1745e
	s_mul_i32 s17, s16, 44
	s_sub_u32 s17, s15, s17
	v_readlane_b32 s4, v248, 7
	v_readlane_b32 s5, v248, 8
	v_readlane_b32 s12, v248, 3
	v_readlane_b32 s13, v248, 4
	s_mov_b32 s6, 0x2c00
	s_mul_i32 s18, s16, 0x58000
	s_lshl_b32 s15, s17, 8
	s_add_u32 s18, s18, s15
	s_add_u32 s4, s4, s18
	s_addc_u32 s5, s5, 0
	s_lshl_b32 s15, s16, 7
	s_add_u32 s12, s12, s15
	s_addc_u32 s13, s13, 0
	s_branch .Ltp43_end
.Ltp43_c2:
	s_cmp_lt_u32 s3, 4224
	s_cbranch_scc0 .Ltp43_c3
	s_sub_u32 s15, s3, 0xb00
	s_lshr_b32 s16, s15, 4
	s_and_b32 s17, s15, 15
	v_readlane_b32 s4, v249, 49
	v_readlane_b32 s5, v249, 50
	v_readlane_b32 s12, v248, 3
	v_readlane_b32 s13, v248, 4
	s_mov_b32 s6, 0x1000
	s_mul_i32 s18, s16, 0x20000
	s_lshl_b32 s15, s17, 8
	s_add_u32 s18, s18, s15
	s_add_u32 s4, s4, s18
	s_addc_u32 s5, s5, 0
	s_branch .Ltp43_end
.Ltp43_c3:
	s_sub_u32 s15, s3, 0x1080
	s_lshr_b32 s16, s15, 4
	s_and_b32 s17, s15, 15
	v_readlane_b32 s4, v249, 53
	v_readlane_b32 s5, v249, 54
	v_readlane_b32 s12, v249, 51
	v_readlane_b32 s13, v249, 52
	s_mov_b32 s6, 0x1000
	s_mul_i32 s18, s16, 0x20000
	s_lshl_b32 s15, s17, 8
	s_add_u32 s18, s18, s15
	s_add_u32 s4, s4, s18
	s_addc_u32 s5, s5, 0
	s_lshl_b32 s15, s16, 7
	s_add_u32 s12, s12, s15
	s_addc_u32 s13, s13, 0
.Ltp43_end:
	s_lshl_b32 s7, s6, 3
	s_nop 0
	v_mad_u32_u24 v4, v1, s7, v0
	s_nop 3
	global_load_dwordx4 v[96:99], v4, s[4:5]
	s_add_u32 s4, s4, s6
	s_addc_u32 s5, s5, 0
	global_load_dwordx4 v[100:103], v4, s[4:5]
	s_add_u32 s4, s4, s6
	s_addc_u32 s5, s5, 0
	global_load_dwordx4 v[104:107], v4, s[4:5]
	s_add_u32 s4, s4, s6
	s_addc_u32 s5, s5, 0
	global_load_dwordx4 v[108:111], v4, s[4:5]
	s_add_u32 s4, s4, s6
	s_addc_u32 s5, s5, 0
	global_load_dwordx4 v[112:115], v4, s[4:5]
	s_add_u32 s4, s4, s6
	s_addc_u32 s5, s5, 0
	global_load_dwordx4 v[116:119], v4, s[4:5]
	s_add_u32 s4, s4, s6
	s_addc_u32 s5, s5, 0
	global_load_dwordx4 v[120:123], v4, s[4:5]
	s_add_u32 s4, s4, s6
	s_addc_u32 s5, s5, 0
	global_load_dwordx4 v[124:127], v4, s[4:5]
	global_load_dwordx4 v[128:131], v3, s[12:13]
	global_load_dwordx4 v[132:135], v3, s[12:13] offset:16
	s_waitcnt vmcnt(20)
	s_cmp_lt_u32 s0, 1408
	s_cbranch_scc0 .Ltp44_c1
	s_mov_b32 s15, s0
	s_mul_hi_u32 s16, s15, 0x5d1745e
	s_mul_i32 s17, s16, 44
	s_sub_u32 s17, s15, s17
	s_mov_b32 s10, 0x800
	s_lshr_b32 s15, s17, 1
	s_lshl_b32 s15, s15, 8
	s_and_b32 s18, s17, 1
	s_lshl_b32 s18, s18, 6
	s_add_u32 s15, s15, s18
	s_mul_i32 s15, s15, s10
	s_lshl_b32 s18, s16, 6
	s_add_u32 s15, s15, s18
	s_add_u32 s15, s15, 0x700000
	s_add_u32 s8, s24, s15
	s_addc_u32 s9, s25, 0
	s_mov_b32 s14, 1
	s_branch .Ltp44_end
.Ltp44_c1:
	s_cmp_lt_u32 s0, 2816
	s_cbranch_scc0 .Ltp44_c2
	s_sub_u32 s15, s0, 0x580
	s_mul_hi_u32 s16, s15, 0x5d1745e
	s_mul_i32 s17, s16, 44
	s_sub_u32 s17, s15, s17
	s_mov_b32 s10, 0x800
	s_lshr_b32 s15, s17, 1
	s_lshl_b32 s15, s15, 8
	s_and_b32 s18, s17, 1
	s_lshl_b32 s18, s18, 6
	s_add_u32 s15, s15, s18
	s_add_u32 s15, s15, 128
	s_mul_i32 s15, s15, s10
	s_lshl_b32 s18, s16, 6
	s_add_u32 s15, s15, s18
	s_add_u32 s15, s15, 0x700000
	s_add_u32 s8, s24, s15
	s_addc_u32 s9, s25, 0
	s_mov_b32 s14, 1
	s_branch .Ltp44_end
.Ltp44_c2:
	s_cmp_lt_u32 s0, 4224
	s_cbranch_scc0 .Ltp44_c3
	s_sub_u32 s15, s0, 0xb00
	s_lshr_b32 s16, s15, 4
	s_and_b32 s17, s15, 15
	s_mov_b32 s10, 0x1600
	s_lshl_b32 s15, s17, 6
	s_mul_i32 s15, s15, s10
	s_lshl_b32 s18, s16, 6
	s_add_u32 s15, s15, s18
	s_add_u32 s15, s15, 0x1200000
	s_add_u32 s8, s24, s15
	s_addc_u32 s9, s25, 0
	s_mov_b32 s14, 0
	s_branch .Ltp44_end
.Ltp44_c3:
	s_sub_u32 s15, s0, 0x1080
	s_lshr_b32 s16, s15, 4
	s_and_b32 s17, s15, 15
	s_mov_b32 s10, 0x800
	s_lshl_b32 s15, s17, 6
	s_mul_i32 s15, s15, s10
	s_lshl_b32 s18, s16, 6
	s_add_u32 s15, s15, s18
	s_add_u32 s15, s15, 0x1780000
	s_add_u32 s8, s24, s15
	s_addc_u32 s9, s25, 0
	s_mov_b32 s14, 1
.Ltp44_end:
	v_mad_u32_u24 v5, v2, s10, v6
	s_cmp_eq_u32 s14, 0
	s_cbranch_scc1 .Ltp45_ng
	v_mul_f32_e32 v16, v16, v48
	v_mul_f32_e32 v17, v17, v48
	v_mul_f32_e32 v18, v18, v48
	v_mul_f32_e32 v19, v19, v48
	v_mul_f32_e32 v20, v20, v49
	v_mul_f32_e32 v21, v21, v49
	v_mul_f32_e32 v22, v22, v49
	v_mul_f32_e32 v23, v23, v49
	v_mul_f32_e32 v24, v24, v50
	v_mul_f32_e32 v25, v25, v50
	v_mul_f32_e32 v26, v26, v50
	v_mul_f32_e32 v27, v27, v50
	v_mul_f32_e32 v28, v28, v51
	v_mul_f32_e32 v29, v29, v51
	v_mul_f32_e32 v30, v30, v51
	v_mul_f32_e32 v31, v31, v51
	v_mul_f32_e32 v32, v32, v52
	v_mul_f32_e32 v33, v33, v52
	v_mul_f32_e32 v34, v34, v52
	v_mul_f32_e32 v35, v35, v52
	v_mul_f32_e32 v36, v36, v53
	v_mul_f32_e32 v37, v37, v53
	v_mul_f32_e32 v38, v38, v53
	v_mul_f32_e32 v39, v39, v53
	v_mul_f32_e32 v40, v40, v54
	v_mul_f32_e32 v41, v41, v54
	v_mul_f32_e32 v42, v42, v54
	v_mul_f32_e32 v43, v43, v54
	v_mul_f32_e32 v44, v44, v55
	v_mul_f32_e32 v45, v45, v55
	v_mul_f32_e32 v46, v46, v55
	v_mul_f32_e32 v47, v47, v55
.Ltp45_ng:
	v_cvt_pk_bf16_f32 v136, v16, v20
	v_cvt_pk_bf16_f32 v137, v24, v28
	v_cvt_pk_bf16_f32 v138, v32, v36
	v_cvt_pk_bf16_f32 v139, v40, v44
	v_cvt_pk_bf16_f32 v140, v17, v21
	v_cvt_pk_bf16_f32 v141, v25, v29
	v_cvt_pk_bf16_f32 v142, v33, v37
	v_cvt_pk_bf16_f32 v143, v41, v45
	v_cvt_pk_bf16_f32 v144, v18, v22
	v_cvt_pk_bf16_f32 v145, v26, v30
	v_cvt_pk_bf16_f32 v146, v34, v38
	v_cvt_pk_bf16_f32 v147, v42, v46
	v_cvt_pk_bf16_f32 v148, v19, v23
	v_cvt_pk_bf16_f32 v149, v27, v31
	v_cvt_pk_bf16_f32 v150, v35, v39
	v_cvt_pk_bf16_f32 v151, v43, v47
	global_store_dwordx4 v5, v[136:139], s[8:9]
	s_add_u32 s8, s8, s10
	s_addc_u32 s9, s9, 0
	global_store_dwordx4 v5, v[140:143], s[8:9]
	s_add_u32 s8, s8, s10
	s_addc_u32 s9, s9, 0
	global_store_dwordx4 v5, v[144:147], s[8:9]
	s_add_u32 s8, s8, s10
	s_addc_u32 s9, s9, 0
	global_store_dwordx4 v5, v[148:151], s[8:9]
	s_add_u32 s11, s0, s1
	s_cmp_lt_u32 s11, 4736
	s_cbranch_scc0 .Ltp4_done
	s_waitcnt vmcnt(14)
	s_cmp_lt_u32 s2, 1408
	s_cbranch_scc0 .Ltp46_c1
	s_mov_b32 s15, s2
	s_mul_hi_u32 s16, s15, 0x5d1745e
	s_mul_i32 s17, s16, 44
	s_sub_u32 s17, s15, s17
	s_mov_b32 s10, 0x800
	s_lshr_b32 s15, s17, 1
	s_lshl_b32 s15, s15, 8
	s_and_b32 s18, s17, 1
	s_lshl_b32 s18, s18, 6
	s_add_u32 s15, s15, s18
	s_mul_i32 s15, s15, s10
	s_lshl_b32 s18, s16, 6
	s_add_u32 s15, s15, s18
	s_add_u32 s15, s15, 0x700000
	s_add_u32 s8, s24, s15
	s_addc_u32 s9, s25, 0
	s_mov_b32 s14, 1
	s_branch .Ltp46_end
.Ltp46_c1:
	s_cmp_lt_u32 s2, 2816
	s_cbranch_scc0 .Ltp46_c2
	s_sub_u32 s15, s2, 0x580
	s_mul_hi_u32 s16, s15, 0x5d1745e
	s_mul_i32 s17, s16, 44
	s_sub_u32 s17, s15, s17
	s_mov_b32 s10, 0x800
	s_lshr_b32 s15, s17, 1
	s_lshl_b32 s15, s15, 8
	s_and_b32 s18, s17, 1
	s_lshl_b32 s18, s18, 6
	s_add_u32 s15, s15, s18
	s_add_u32 s15, s15, 128
	s_mul_i32 s15, s15, s10
	s_lshl_b32 s18, s16, 6
	s_add_u32 s15, s15, s18
	s_add_u32 s15, s15, 0x700000
	s_add_u32 s8, s24, s15
	s_addc_u32 s9, s25, 0
	s_mov_b32 s14, 1
	s_branch .Ltp46_end
.Ltp46_c2:
	s_cmp_lt_u32 s2, 4224
	s_cbranch_scc0 .Ltp46_c3
	s_sub_u32 s15, s2, 0xb00
	s_lshr_b32 s16, s15, 4
	s_and_b32 s17, s15, 15
	s_mov_b32 s10, 0x1600
	s_lshl_b32 s15, s17, 6
	s_mul_i32 s15, s15, s10
	s_lshl_b32 s18, s16, 6
	s_add_u32 s15, s15, s18
	s_add_u32 s15, s15, 0x1200000
	s_add_u32 s8, s24, s15
	s_addc_u32 s9, s25, 0
	s_mov_b32 s14, 0
	s_branch .Ltp46_end
.Ltp46_c3:
	s_sub_u32 s15, s2, 0x1080
	s_lshr_b32 s16, s15, 4
	s_and_b32 s17, s15, 15
	s_mov_b32 s10, 0x800
	s_lshl_b32 s15, s17, 6
	s_mul_i32 s15, s15, s10
	s_lshl_b32 s18, s16, 6
	s_add_u32 s15, s15, s18
	s_add_u32 s15, s15, 0x1780000
	s_add_u32 s8, s24, s15
	s_addc_u32 s9, s25, 0
	s_mov_b32 s14, 1
.Ltp46_end:
	v_mad_u32_u24 v5, v2, s10, v6
	s_cmp_eq_u32 s14, 0
	s_cbranch_scc1 .Ltp47_ng
	v_mul_f32_e32 v56, v56, v88
	v_mul_f32_e32 v57, v57, v88
	v_mul_f32_e32 v58, v58, v88
	v_mul_f32_e32 v59, v59, v88
	v_mul_f32_e32 v60, v60, v89
	v_mul_f32_e32 v61, v61, v89
	v_mul_f32_e32 v62, v62, v89
	v_mul_f32_e32 v63, v63, v89
	v_mul_f32_e32 v64, v64, v90
	v_mul_f32_e32 v65, v65, v90
	v_mul_f32_e32 v66, v66, v90
	v_mul_f32_e32 v67, v67, v90
	v_mul_f32_e32 v68, v68, v91
	v_mul_f32_e32 v69, v69, v91
	v_mul_f32_e32 v70, v70, v91
	v_mul_f32_e32 v71, v71, v91
	v_mul_f32_e32 v72, v72, v92
	v_mul_f32_e32 v73, v73, v92
	v_mul_f32_e32 v74, v74, v92
	v_mul_f32_e32 v75, v75, v92
	v_mul_f32_e32 v76, v76, v93
	v_mul_f32_e32 v77, v77, v93
	v_mul_f32_e32 v78, v78, v93
	v_mul_f32_e32 v79, v79, v93
	v_mul_f32_e32 v80, v80, v94
	v_mul_f32_e32 v81, v81, v94
	v_mul_f32_e32 v82, v82, v94
	v_mul_f32_e32 v83, v83, v94
	v_mul_f32_e32 v84, v84, v95
	v_mul_f32_e32 v85, v85, v95
	v_mul_f32_e32 v86, v86, v95
	v_mul_f32_e32 v87, v87, v95
.Ltp47_ng:
	v_cvt_pk_bf16_f32 v136, v56, v60
	v_cvt_pk_bf16_f32 v137, v64, v68
	v_cvt_pk_bf16_f32 v138, v72, v76
	v_cvt_pk_bf16_f32 v139, v80, v84
	v_cvt_pk_bf16_f32 v140, v57, v61
	v_cvt_pk_bf16_f32 v141, v65, v69
	v_cvt_pk_bf16_f32 v142, v73, v77
	v_cvt_pk_bf16_f32 v143, v81, v85
	v_cvt_pk_bf16_f32 v144, v58, v62
	v_cvt_pk_bf16_f32 v145, v66, v70
	v_cvt_pk_bf16_f32 v146, v74, v78
	v_cvt_pk_bf16_f32 v147, v82, v86
	v_cvt_pk_bf16_f32 v148, v59, v63
	v_cvt_pk_bf16_f32 v149, v67, v71
	v_cvt_pk_bf16_f32 v150, v75, v79
	v_cvt_pk_bf16_f32 v151, v83, v87
	global_store_dwordx4 v5, v[136:139], s[8:9]
	s_add_u32 s8, s8, s10
	s_addc_u32 s9, s9, 0
	global_store_dwordx4 v5, v[140:143], s[8:9]
	s_add_u32 s8, s8, s10
	s_addc_u32 s9, s9, 0
	global_store_dwordx4 v5, v[144:147], s[8:9]
	s_add_u32 s8, s8, s10
	s_addc_u32 s9, s9, 0
	global_store_dwordx4 v5, v[148:151], s[8:9]
	s_add_u32 s11, s11, s1
	s_cmp_lt_u32 s11, 4736
	s_cbranch_scc0 .Ltp4_done
	s_waitcnt vmcnt(8)
	s_cmp_lt_u32 s3, 1408
	s_cbranch_scc0 .Ltp48_c1
	s_mov_b32 s15, s3
	s_mul_hi_u32 s16, s15, 0x5d1745e
	s_mul_i32 s17, s16, 44
	s_sub_u32 s17, s15, s17
	s_mov_b32 s10, 0x800
	s_lshr_b32 s15, s17, 1
	s_lshl_b32 s15, s15, 8
	s_and_b32 s18, s17, 1
	s_lshl_b32 s18, s18, 6
	s_add_u32 s15, s15, s18
	s_mul_i32 s15, s15, s10
	s_lshl_b32 s18, s16, 6
	s_add_u32 s15, s15, s18
	s_add_u32 s15, s15, 0x700000
	s_add_u32 s8, s24, s15
	s_addc_u32 s9, s25, 0
	s_mov_b32 s14, 1
	s_branch .Ltp48_end
.Ltp48_c1:
	s_cmp_lt_u32 s3, 2816
	s_cbranch_scc0 .Ltp48_c2
	s_sub_u32 s15, s3, 0x580
	s_mul_hi_u32 s16, s15, 0x5d1745e
	s_mul_i32 s17, s16, 44
	s_sub_u32 s17, s15, s17
	s_mov_b32 s10, 0x800
	s_lshr_b32 s15, s17, 1
	s_lshl_b32 s15, s15, 8
	s_and_b32 s18, s17, 1
	s_lshl_b32 s18, s18, 6
	s_add_u32 s15, s15, s18
	s_add_u32 s15, s15, 128
	s_mul_i32 s15, s15, s10
	s_lshl_b32 s18, s16, 6
	s_add_u32 s15, s15, s18
	s_add_u32 s15, s15, 0x700000
	s_add_u32 s8, s24, s15
	s_addc_u32 s9, s25, 0
	s_mov_b32 s14, 1
	s_branch .Ltp48_end
.Ltp48_c2:
	s_cmp_lt_u32 s3, 4224
	s_cbranch_scc0 .Ltp48_c3
	s_sub_u32 s15, s3, 0xb00
	s_lshr_b32 s16, s15, 4
	s_and_b32 s17, s15, 15
	s_mov_b32 s10, 0x1600
	s_lshl_b32 s15, s17, 6
	s_mul_i32 s15, s15, s10
	s_lshl_b32 s18, s16, 6
	s_add_u32 s15, s15, s18
	s_add_u32 s15, s15, 0x1200000
	s_add_u32 s8, s24, s15
	s_addc_u32 s9, s25, 0
	s_mov_b32 s14, 0
	s_branch .Ltp48_end
.Ltp48_c3:
	s_sub_u32 s15, s3, 0x1080
	s_lshr_b32 s16, s15, 4
	s_and_b32 s17, s15, 15
	s_mov_b32 s10, 0x800
	s_lshl_b32 s15, s17, 6
	s_mul_i32 s15, s15, s10
	s_lshl_b32 s18, s16, 6
	s_add_u32 s15, s15, s18
	s_add_u32 s15, s15, 0x1780000
	s_add_u32 s8, s24, s15
	s_addc_u32 s9, s25, 0
	s_mov_b32 s14, 1
.Ltp48_end:
	v_mad_u32_u24 v5, v2, s10, v6
	s_cmp_eq_u32 s14, 0
	s_cbranch_scc1 .Ltp49_ng
	v_mul_f32_e32 v96, v96, v128
	v_mul_f32_e32 v97, v97, v128
	v_mul_f32_e32 v98, v98, v128
	v_mul_f32_e32 v99, v99, v128
	v_mul_f32_e32 v100, v100, v129
	v_mul_f32_e32 v101, v101, v129
	v_mul_f32_e32 v102, v102, v129
	v_mul_f32_e32 v103, v103, v129
	v_mul_f32_e32 v104, v104, v130
	v_mul_f32_e32 v105, v105, v130
	v_mul_f32_e32 v106, v106, v130
	v_mul_f32_e32 v107, v107, v130
	v_mul_f32_e32 v108, v108, v131
	v_mul_f32_e32 v109, v109, v131
	v_mul_f32_e32 v110, v110, v131
	v_mul_f32_e32 v111, v111, v131
	v_mul_f32_e32 v112, v112, v132
	v_mul_f32_e32 v113, v113, v132
	v_mul_f32_e32 v114, v114, v132
	v_mul_f32_e32 v115, v115, v132
	v_mul_f32_e32 v116, v116, v133
	v_mul_f32_e32 v117, v117, v133
	v_mul_f32_e32 v118, v118, v133
	v_mul_f32_e32 v119, v119, v133
	v_mul_f32_e32 v120, v120, v134
	v_mul_f32_e32 v121, v121, v134
	v_mul_f32_e32 v122, v122, v134
	v_mul_f32_e32 v123, v123, v134
	v_mul_f32_e32 v124, v124, v135
	v_mul_f32_e32 v125, v125, v135
	v_mul_f32_e32 v126, v126, v135
	v_mul_f32_e32 v127, v127, v135
.Ltp49_ng:
	v_cvt_pk_bf16_f32 v136, v96, v100
	v_cvt_pk_bf16_f32 v137, v104, v108
	v_cvt_pk_bf16_f32 v138, v112, v116
	v_cvt_pk_bf16_f32 v139, v120, v124
	v_cvt_pk_bf16_f32 v140, v97, v101
	v_cvt_pk_bf16_f32 v141, v105, v109
	v_cvt_pk_bf16_f32 v142, v113, v117
	v_cvt_pk_bf16_f32 v143, v121, v125
	v_cvt_pk_bf16_f32 v144, v98, v102
	v_cvt_pk_bf16_f32 v145, v106, v110
	v_cvt_pk_bf16_f32 v146, v114, v118
	v_cvt_pk_bf16_f32 v147, v122, v126
	v_cvt_pk_bf16_f32 v148, v99, v103
	v_cvt_pk_bf16_f32 v149, v107, v111
	v_cvt_pk_bf16_f32 v150, v115, v119
	v_cvt_pk_bf16_f32 v151, v123, v127
	global_store_dwordx4 v5, v[136:139], s[8:9]
	s_add_u32 s8, s8, s10
	s_addc_u32 s9, s9, 0
	global_store_dwordx4 v5, v[140:143], s[8:9]
	s_add_u32 s8, s8, s10
	s_addc_u32 s9, s9, 0
	global_store_dwordx4 v5, v[144:147], s[8:9]
	s_add_u32 s8, s8, s10
	s_addc_u32 s9, s9, 0
	global_store_dwordx4 v5, v[148:151], s[8:9]
	s_add_u32 s0, s11, s1
	s_branch .Ltp4_loop
